# phase 3 (HGRN combine) fused behind each workgroup's last mixer item: chain done-counter + acquire instead of one grid barrier
# speedup vs baseline: 1.0072x; 1.0072x over previous
; DI void phase_prep(const Params& p) {
;   const int tid = threadIdx.x, lane = tid & 63, wave = tid >> 6;
;   if (blockIdx.x == 0 && tid == 0) *(unsigned*)(p.ws + WS_END) = 0u;
;   { float* RS = (float*)(p.ws + WS_END + 8192); const int i = blockIdx.x * 512 + tid; if (i < NTOK) RS[i] = 0.f; }
.LBB0_17:
	s_or_b64 exec, exec, s[4:5]
	v_or_b32_e32 v0, s2, v202
	v_cmp_eq_u32_e32 vcc, 0, v0
	s_and_saveexec_b64 s[4:5], vcc
	s_cbranch_execz .LBB0_19
	v_mov_b32_e32 v0, 0x32000000
	v_mov_b32_e32 v1, 0
	global_store_dword v0, v1, s[58:59]
	global_store_dword v0, v1, s[58:59] offset:64

; DI void phase_mixer(const Params& p) {
;     ...
;   for (;;) {
;     __syncthreads();
;     if (threadIdx.x == 0) *sItem = (int)atomicAdd(ctr, 1u);
;     __syncthreads();
;     const int it = *sItem;
;     if (it >= 48 + 2048) break;
;     if (it < 48) hgrn_item(p, it); else attn_item(p, it - 48);
;   }
.Lhg_done:
	s_waitcnt vmcnt(0)
	s_barrier
	v_readlane_b32 s84, v236, 5
	v_readlane_b32 s85, v236, 6
	s_nop 3
	s_and_saveexec_b64 s[0:1], s[84:85]
	s_cbranch_execz .Lhg_sig_done
	buffer_wbl2 sc1
	s_waitcnt vmcnt(0)
	v_mov_b32_e32 v0, 0
	v_mov_b32_e32 v1, 1
	global_atomic_add v0, v1, s[82:83] offset:64
.Lhg_sig_done:
	s_or_b64 exec, exec, s[0:1]
.LBB0_952:
	v_readlane_b32 s84, v236, 5
	s_mov_b64 s[0:1], 0
	v_readlane_b32 s85, v236, 6

; DI void phase_mixer(const Params& p) {
;     ...
;   for (;;) {
;     __syncthreads();
;     if (threadIdx.x == 0) *sItem = (int)atomicAdd(ctr, 1u);
;     __syncthreads();
;     const int it = *sItem;
;     if (it >= 48 + 2048) break;
;     if (it < 48) hgrn_item(p, it); else attn_item(p, it - 48);
;   }
; }
.LBB0_1009:
	s_waitcnt vmcnt(0)
	s_barrier
	v_readlane_b32 s48, v236, 12
	v_readlane_b32 s72, v236, 8
	v_readlane_b32 s49, v236, 13
	v_readlane_b32 s70, v236, 11
	v_readlane_b32 s71, v236, 10
	v_readlane_b32 s73, v236, 9
	v_readlane_b32 s74, v236, 1
	v_readlane_b32 s78, v236, 7
	v_readlane_b32 s75, v236, 2
	s_and_saveexec_b64 s[0:1], s[84:85]
	s_cbranch_execz .LBB0_1061
	v_mov_b32_e32 v0, 0
.Lhgw_spin:
	global_load_dword v1, v0, s[82:83] offset:64 sc1
	s_waitcnt vmcnt(0)
	v_readfirstlane_b32 s3, v1
	s_cmp_ge_u32 s3, 48
	s_cbranch_scc1 .Lhgw_ok
	s_sleep 1
	s_branch .Lhgw_spin
.Lhgw_ok:
	buffer_inv sc1
	s_waitcnt vmcnt(0)
